# unit scheduler: emulated division by gsz=min(nM-fm,wgm) (always wgm=8/4 for these shapes) replaced by shift+mask in the 7 per-tile headers
# baseline (speedup 1.0000x reference)
.LBB0_85:
	s_ashr_i32 s4, s6, 3
	s_add_i32 s4, s10, s4
	s_ashr_i32 s5, s4, 31
	s_lshr_b32 s5, s5, 25
	s_add_i32 s5, s4, s5
	s_ashr_i32 s6, s5, 7
	s_lshl_b32 s6, s6, 3
	s_and_b32 s5, s5, 0xffffff80
	s_sub_i32 s5, s4, s5
	s_ashr_i32 s4, s5, 3
	s_and_b32 s5, s5, 7
	s_add_i32 s6, s6, s5

.LBB0_198:
	s_ashr_i32 s5, s5, 3
	s_add_i32 s5, s9, s5
	s_ashr_i32 s6, s5, 31
	s_lshr_b32 s6, s6, 24
	s_add_i32 s6, s5, s6
	s_ashr_i32 s7, s6, 8
	s_lshl_b32 s7, s7, 3
	s_and_b32 s6, s6, 0xffffff00
	s_sub_i32 s5, s5, s6
	s_ashr_i32 s6, s5, 3
	s_and_b32 s5, s5, 7
	s_add_i32 s8, s7, s5

.LBB0_214:
	s_add_i32 s31, s31, 1
	v_readlane_b32 s0, v254, 4
	v_readlane_b32 s5, v254, 5
	s_mul_i32 s0, s31, s0
	s_mul_hi_u32 s1, s31, s5
	s_add_i32 s1, s1, s0
	s_mul_i32 s0, s31, s5
	s_add_u32 s8, s0, s20
	s_addc_u32 s9, s1, s27
	v_mov_b64_e32 v[0:1], 0x15ff
	v_cmp_gt_i64_e64 s[0:1], s[8:9], v[0:1]
	s_and_b64 vcc, exec, s[0:1]
	s_cbranch_vccnz .LBB0_216
	s_ashr_i32 s4, s8, 31
	s_lshr_b32 s4, s4, 29
	s_add_i32 s4, s8, s4
	s_ashr_i32 s5, s4, 3
	s_and_b32 s4, s4, -8
	s_sub_i32 s4, s8, s4
	s_cmp_lt_i32 s4, 0
	s_movk_i32 s6, 0x2c1
	s_cselect_b32 s6, s6, 0x2c0
	s_mul_i32 s4, s6, s4
	s_add_i32 s4, s4, s5
	s_mul_hi_i32 s5, s4, 0x2e8ba2e9
	s_lshr_b32 s6, s5, 31
	s_ashr_i32 s5, s5, 6
	s_add_i32 s5, s5, s6
	s_lshl_b32 s6, s5, 3
	s_mulk_i32 s5, 0x160
	s_sub_i32 s5, s4, s5
	s_ashr_i32 s4, s5, 3
	s_and_b32 s5, s5, 7
	s_add_i32 s6, s5, s6

.LBB0_240:
	s_ashr_i32 s6, s14, 3
	s_add_i32 s6, s38, s6
	s_ashr_i32 s7, s6, 31
	s_lshr_b32 s7, s7, 27
	s_add_i32 s7, s6, s7
	s_ashr_i32 s14, s7, 5
	s_lshl_b32 s14, s14, 2
	s_andn2_b32 s7, s7, 31
	s_sub_i32 s6, s6, s7
	s_ashr_i32 s38, s6, 2
	s_and_b32 s6, s6, 3
	s_add_i32 s39, s14, s6

.LBB0_266:
	s_ashr_i32 s6, s12, 3
	s_add_i32 s6, s14, s6
	s_ashr_i32 s7, s6, 31
	s_lshr_b32 s7, s7, 27
	s_add_i32 s7, s6, s7
	s_ashr_i32 s12, s7, 5
	s_lshl_b32 s12, s12, 2
	s_andn2_b32 s7, s7, 31
	s_sub_i32 s6, s6, s7
	s_ashr_i32 s35, s6, 2
	s_and_b32 s6, s6, 3
	s_add_i32 s36, s12, s6

.LBB0_292:
	s_ashr_i32 s4, s6, 3
	s_add_i32 s4, s10, s4
	s_ashr_i32 s5, s4, 31
	s_lshr_b32 s5, s5, 27
	s_add_i32 s5, s4, s5
	s_ashr_i32 s6, s5, 5
	s_lshl_b32 s6, s6, 2
	s_andn2_b32 s5, s5, 31
	s_sub_i32 s5, s4, s5
	s_ashr_i32 s4, s5, 2
	s_and_b32 s5, s5, 3
	s_add_i32 s6, s6, s5

.LBB0_412:
	s_add_i32 s37, s37, 1
	v_readlane_b32 s0, v254, 4
	v_readlane_b32 s7, v254, 5
	s_mul_i32 s0, s37, s0
	s_mul_hi_u32 s1, s37, s7
	s_add_i32 s1, s1, s0
	s_mul_i32 s0, s37, s7
	s_add_u32 s10, s0, s22
	s_addc_u32 s11, s1, s29
	v_cmp_gt_i64_e64 s[0:1], s[10:11], v[200:201]
	s_and_b64 vcc, exec, s[0:1]
	s_cbranch_vccnz .LBB0_414
	s_ashr_i32 s6, s10, 31
	s_lshr_b32 s6, s6, 29
	s_add_i32 s6, s10, s6
	s_ashr_i32 s7, s6, 3
	s_and_b32 s6, s6, -8
	s_sub_i32 s6, s10, s6
	s_cmp_lt_i32 s6, 0
	s_movk_i32 s8, 0x121
	s_cselect_b32 s8, s8, 0x120
	s_mul_i32 s6, s8, s6
	s_add_i32 s6, s6, s7
	s_mul_hi_i32 s7, s6, 0x38e38e39
	s_lshr_b32 s8, s7, 31
	s_ashr_i32 s7, s7, 6
	s_add_i32 s7, s7, s8
	s_lshl_b32 s8, s7, 2
	s_mulk_i32 s7, 0x120
	s_sub_i32 s7, s6, s7
	s_ashr_i32 s6, s7, 2
	s_and_b32 s7, s7, 3
	s_add_i32 s8, s7, s8
